# grid barrier: XCD leader publishes the per-XCD generation with a plain store (L2-resident) instead of a memory-side atomic
# speedup vs baseline: 1.0160x; 1.0027x over previous
.LBB0_176:
	s_andn2_saveexec_b64 s[0:1], s[8:9]
	s_cbranch_execz .LBB0_196
	v_readfirstlane_b32 s99, v1
	s_mov_b64 s[8:9], exec
	buffer_wbl2 sc1
	s_waitcnt lgkmcnt(0)
	s_waitcnt vmcnt(0)
	buffer_inv sc1
	v_mbcnt_lo_u32_b32 v1, s8, 0
	v_mbcnt_hi_u32_b32 v1, s9, v1
	v_cmp_eq_u32_e32 vcc, 0, v1
	s_and_saveexec_b64 s[10:11], vcc
	s_cbranch_execz .LBB0_179
	s_bcnt1_i32_b64 s0, s[8:9]
	v_mov_b32_e32 v3, s0
	v_readlane_b32 s0, v253, 10
	v_mov_b32_e32 v2, 0xf681000
	v_readlane_b32 s1, v253, 11
	s_nop 4
	global_atomic_add v2, v2, v3, s[0:1] offset:1280 sc0

.LBB0_193:
	s_or_b64 exec, exec, s[8:9]
	s_mov_b64 s[8:9], exec
	v_mbcnt_lo_u32_b32 v0, s8, 0
	v_mbcnt_hi_u32_b32 v0, s9, v0
	v_cmp_eq_u32_e32 vcc, 0, v0
	s_waitcnt vmcnt(0)
	s_and_saveexec_b64 s[10:11], vcc
	s_cbranch_execz .LBB0_195
	s_bcnt1_i32_b64 s0, s[8:9]
	v_mov_b32_e32 v0, 0x2000
	s_add_u32 s99, s99, 1
	v_mov_b32_e32 v1, s99
	global_store_dword v0, v1, s[6:7] offset:1024

.LBB0_263:
	s_andn2_saveexec_b64 s[0:1], s[10:11]
	s_cbranch_execz .LBB0_283
	v_readfirstlane_b32 s99, v1
	s_mov_b64 s[10:11], exec
	buffer_wbl2 sc1
	s_waitcnt lgkmcnt(0)
	s_waitcnt vmcnt(0)
	buffer_inv sc1
	v_mbcnt_lo_u32_b32 v1, s10, 0
	v_mbcnt_hi_u32_b32 v1, s11, v1
	v_cmp_eq_u32_e32 vcc, 0, v1
	s_and_saveexec_b64 s[12:13], vcc
	s_cbranch_execz .LBB0_266
	s_bcnt1_i32_b64 s0, s[10:11]
	v_mov_b32_e32 v3, s0
	v_readlane_b32 s0, v253, 10
	v_mov_b32_e32 v2, 0xf681000
	v_readlane_b32 s1, v253, 11
	s_nop 4
	global_atomic_add v2, v2, v3, s[0:1] offset:1280 sc0

.LBB0_280:
	s_or_b64 exec, exec, s[10:11]
	s_mov_b64 s[10:11], exec
	v_mbcnt_lo_u32_b32 v0, s10, 0
	v_mbcnt_hi_u32_b32 v0, s11, v0
	v_cmp_eq_u32_e32 vcc, 0, v0
	s_waitcnt vmcnt(0)
	s_and_saveexec_b64 s[12:13], vcc
	s_cbranch_execz .LBB0_282
	s_bcnt1_i32_b64 s0, s[10:11]
	v_mov_b32_e32 v0, 0x2000
	s_add_u32 s99, s99, 1
	v_mov_b32_e32 v1, s99
	global_store_dword v0, v1, s[8:9] offset:1024

.LBB0_652:
	s_andn2_saveexec_b64 s[0:1], s[12:13]
	s_cbranch_execz .LBB0_672
	v_readfirstlane_b32 s99, v1
	s_mov_b64 s[12:13], exec
	buffer_wbl2 sc1
	s_waitcnt lgkmcnt(0)
	s_waitcnt vmcnt(0)
	buffer_inv sc1
	v_mbcnt_lo_u32_b32 v1, s12, 0
	v_mbcnt_hi_u32_b32 v1, s13, v1
	v_cmp_eq_u32_e32 vcc, 0, v1
	s_and_saveexec_b64 s[14:15], vcc
	s_cbranch_execz .LBB0_655
	s_bcnt1_i32_b64 s0, s[12:13]
	v_mov_b32_e32 v3, s0
	v_readlane_b32 s0, v253, 10
	v_mov_b32_e32 v2, 0xf681000
	v_readlane_b32 s1, v253, 11
	s_nop 4
	global_atomic_add v2, v2, v3, s[0:1] offset:1280 sc0

.LBB0_669:
	s_or_b64 exec, exec, s[12:13]
	s_mov_b64 s[12:13], exec
	v_mbcnt_lo_u32_b32 v0, s12, 0
	v_mbcnt_hi_u32_b32 v0, s13, v0
	v_cmp_eq_u32_e32 vcc, 0, v0
	s_waitcnt vmcnt(0)
	s_and_saveexec_b64 s[14:15], vcc
	s_cbranch_execz .LBB0_671
	s_bcnt1_i32_b64 s0, s[12:13]
	v_mov_b32_e32 v0, 0x2000
	s_add_u32 s99, s99, 1
	v_mov_b32_e32 v1, s99
	global_store_dword v0, v1, s[10:11] offset:1024

.LBB0_717:
	s_andn2_saveexec_b64 s[0:1], s[14:15]
	s_cbranch_execz .LBB0_737
	v_readfirstlane_b32 s99, v1
	s_mov_b64 s[14:15], exec
	buffer_wbl2 sc1
	s_waitcnt lgkmcnt(0)
	s_waitcnt vmcnt(0)
	buffer_inv sc1
	v_mbcnt_lo_u32_b32 v1, s14, 0
	v_mbcnt_hi_u32_b32 v1, s15, v1
	v_cmp_eq_u32_e32 vcc, 0, v1
	s_and_saveexec_b64 s[16:17], vcc
	s_cbranch_execz .LBB0_720
	s_bcnt1_i32_b64 s0, s[14:15]
	v_mov_b32_e32 v3, s0
	v_readlane_b32 s0, v253, 10
	v_mov_b32_e32 v2, 0xf681000
	v_readlane_b32 s1, v253, 11
	s_nop 4
	global_atomic_add v2, v2, v3, s[0:1] offset:1280 sc0

.LBB0_734:
	s_or_b64 exec, exec, s[14:15]
	s_mov_b64 s[14:15], exec
	v_mbcnt_lo_u32_b32 v0, s14, 0
	v_mbcnt_hi_u32_b32 v0, s15, v0
	v_cmp_eq_u32_e32 vcc, 0, v0
	s_waitcnt vmcnt(0)
	s_and_saveexec_b64 s[16:17], vcc
	s_cbranch_execz .LBB0_736
	s_bcnt1_i32_b64 s0, s[14:15]
	v_mov_b32_e32 v0, 0x2000
	s_add_u32 s99, s99, 1
	v_mov_b32_e32 v1, s99
	global_store_dword v0, v1, s[12:13] offset:1024
